# fused norm tail: row-sum slots read with plain (L2-served) loads when the placement check holds, agent-scope loads otherwise
# baseline (speedup 1.0000x reference)
; __device__ __forceinline__ int otid() { int t = (int)threadIdx.x; asm volatile("" : "+v"(t)); return t; }
; __device__ __forceinline__ void fused_norm_tail(CA& A, int l, int s) {
;     const int nsite = 3 * l + (s == 1 ? 1 : (s == 4 ? 2 : 3));
;     if (nsite >= 3 * DEPTH) return;
;     const int tid = otid(), lane = tid & 63, wave = __builtin_amdgcn_readfirstlane(tid >> 6);
;     pg8::StaticOrder S; S.init(M, DM, (int)gridDim.x, (int)blockIdx.x); pg8::Unit u;
;     if (!S.next(0, u)) return;
;     unsigned char* const ws = A.ws;
;     const int nl = nsite / 3, nw = nsite % 3, b = u.pm >> 4;
;     const float* slots = (const float*)(ws + WS_RSP) + (size_t)nsite * M * 16;
;     unsigned* cnt = (unsigned*)(ws + WS_PCNT) + ((size_t)nsite * 64 + u.pm) * 16;
;     asm volatile("s_waitcnt vmcnt(0)" ::: "memory");
;     __syncthreads();
;     const float* MODn = (const float*)(ws + WS_MOD) + (size_t)(nl * 4 + b) * NMODC + (3 * nw) * DM;
;     const int col = u.pn * 256 + 4 * lane;
;     const float* hbase = A.out; bf16_t* xn = (bf16_t*)(ws + WS_XN);
;     f32x4 hrow[32];
; #pragma unroll
;     for (int r = 0; r < 32; ++r) hrow[r] = *(const f32x4*)(hbase + (size_t)(u.pm * 256 + wave * 32 + r) * DM + col);
;     const f32x4 ca = *(const f32x4*)(A.norm_g + (size_t)nsite * DM + col) * (1.0f + *(const f32x4*)(MODn + DM + col)), cb = *(const f32x4*)(MODn + col);
;     if (tid == 0) {
;         __hip_atomic_fetch_add(cnt, 1u, __ATOMIC_RELAXED, __HIP_MEMORY_SCOPE_AGENT);
;         unsigned spins = 0;
;         while (__hip_atomic_load(cnt, __ATOMIC_RELAXED, __HIP_MEMORY_SCOPE_AGENT) < 4u) { __builtin_amdgcn_s_sleep(2); if (++spins > (1u << 22)) break; }
;     }
.Lmy_tail:
	v_mov_b32_e32 v1, 0x20018
	ds_read_b32 v1, v1
	v_readlane_b32 s4, v237, 63
	v_readlane_b32 s5, v236, 0
	v_readlane_b32 s12, v237, 62
	v_readfirstlane_b32 s18, v179
	s_load_dwordx2 s[8:9], s[4:5], 0xc8
	s_load_dwordx2 s[10:11], s[4:5], 0x20
	s_and_b32 s13, s12, 7
	s_lshl_b32 s13, s13, 3
	s_bfe_u32 s14, s12, 0x30003
	s_add_i32 s13, s13, s14
	s_lshr_b32 s14, s12, 6
	s_mul_i32 s15, s80, 0x5556
	s_lshr_b32 s15, s15, 16
	s_mul_i32 s16, s15, 3
	s_sub_i32 s16, s80, s16
	s_lshr_b32 s17, s13, 4
	s_lshr_b32 s18, s18, 6
	s_lshr_b32 s19, s18, 2
	s_and_b32 s20, s18, 3
	v_and_b32_e32 v212, 63, v179
	v_and_b32_e32 v213, 15, v212
	v_lshrrev_b32_e32 v214, 4, v212
	s_lshl_b32 s24, s14, 8
	s_lshl_b32 s25, s20, 5
	s_add_i32 s24, s24, s25
	v_lshl_add_u32 v215, v214, 3, s24
	v_lshlrev_b32_e32 v211, 2, v215
	s_waitcnt lgkmcnt(0)
	v_readfirstlane_b32 s49, v1
	s_lshl_b32 s25, s80, 12
	s_add_u32 s26, s10, s25
	s_addc_u32 s27, s11, 0
	s_lshl_b32 s25, s15, 2
	s_add_i32 s25, s25, s17
	s_mul_i32 s25, s25, 0x9000
	s_mul_i32 s28, s16, 0x3000
	s_add_i32 s25, s25, s28
	s_add_i32 s25, s25, 0x10000
	s_add_u32 s28, s8, s25
	s_addc_u32 s29, s9, 0
	s_add_u32 s30, s28, 0x1000
	s_addc_u32 s31, s29, 0
	s_lshl_b32 s25, s80, 6
	s_add_i32 s25, s25, s13
	s_lshl_b32 s25, s25, 6
	s_add_i32 s25, s25, 0x8000
	s_add_u32 s46, s8, s25
	s_addc_u32 s47, s9, 0
	s_lshl_b32 s25, s80, 20
	s_add_u32 s42, s8, s25
	s_addc_u32 s43, s9, 0
	s_add_u32 s42, s42, 0xed00000
	s_addc_u32 s43, s43, 0
	s_lshl_b32 s25, s13, 8
	s_lshl_b32 s48, s19, 6
	s_add_i32 s25, s25, s48
	s_lshl_b32 s48, s25, 11
	s_add_u32 s38, s8, s48
	s_addc_u32 s39, s9, 0
	s_add_u32 s38, s38, 0x5500000
	s_addc_u32 s39, s39, 0
	s_waitcnt vmcnt(0)
	s_barrier
	global_load_dwordx4 v[130:133], v211, s[26:27]
	global_load_dwordx4 v[146:149], v211, s[30:31]
	global_load_dwordx4 v[162:165], v211, s[28:29]
	global_load_dwordx4 v[134:137], v211, s[26:27] offset:16
	global_load_dwordx4 v[150:153], v211, s[30:31] offset:16
	global_load_dwordx4 v[166:169], v211, s[28:29] offset:16
	global_load_dwordx4 v[138:141], v211, s[26:27] offset:512
	global_load_dwordx4 v[154:157], v211, s[30:31] offset:512
	global_load_dwordx4 v[170:173], v211, s[28:29] offset:512
	global_load_dwordx4 v[142:145], v211, s[26:27] offset:528
	global_load_dwordx4 v[158:161], v211, s[30:31] offset:528
	global_load_dwordx4 v[174:177], v211, s[28:29] offset:528
	s_mov_b64 s[4:5], exec
	v_readlane_b32 s6, v238, 8
	v_readlane_b32 s7, v238, 9
	s_nop 1
	s_and_b64 s[6:7], s[4:5], s[6:7]
	s_mov_b64 exec, s[6:7]
	s_cbranch_execz .Lmy_tail_arrived
	v_mov_b32_e32 v1, 1
	s_mov_b32 s48, 0
	global_atomic_add v0, v1, s[46:47]

; __device__ __forceinline__ void fused_norm_tail(CA& A, int l, int s) {
;     ...
;     const f32x4 ca = *(const f32x4*)(A.norm_g + (size_t)nsite * DM + col) * (1.0f + *(const f32x4*)(MODn + DM + col)), cb = *(const f32x4*)(MODn + col);
;     if (tid == 0) {
;         __hip_atomic_fetch_add(cnt, 1u, __ATOMIC_RELAXED, __HIP_MEMORY_SCOPE_AGENT);
;         unsigned spins = 0;
;         while (__hip_atomic_load(cnt, __ATOMIC_RELAXED, __HIP_MEMORY_SCOPE_AGENT) < 4u) { __builtin_amdgcn_s_sleep(2); if (++spins > (1u << 22)) break; }
;     }
;     __syncthreads();
;     float rstd_l = 0.f;
;     {
;         const int row = u.pm * 256 + wave * 32 + (lane & 31);
;         float ss = 0.f;
; #pragma unroll
;         for (int t = 0; t < 4; ++t) {
;             const unsigned long long* sp = (const unsigned long long*)(slots + ((size_t)t * M + row) * 4);
;             const unsigned long long w0 = __hip_atomic_load(sp, __ATOMIC_RELAXED, __HIP_MEMORY_SCOPE_AGENT), w1 = __hip_atomic_load(sp + 1, __ATOMIC_RELAXED, __HIP_MEMORY_SCOPE_AGENT);
;             ss += (__uint_as_float((unsigned)w0) + __uint_as_float((unsigned)(w0 >> 32))) + (__uint_as_float((unsigned)w1) + __uint_as_float((unsigned)(w1 >> 32)));
;         }
;         rstd_l = rsqrtf(ss * (1.0f / DM) + EPS);
;     }
; #pragma unroll
;     for (int r = 0; r < 32; ++r) {
;         const int row = u.pm * 256 + wave * 32 + r;
;         const float rstd = __builtin_bit_cast(float, __builtin_amdgcn_readlane(__builtin_bit_cast(int, rstd_l), r));
.Lmy_tail_arrived:
	s_mov_b64 exec, s[4:5]
	s_waitcnt vmcnt(0)
	v_pk_add_f32 v[146:147], v[146:147], 1.0 op_sel_hi:[1,0]
	v_pk_add_f32 v[148:149], v[148:149], 1.0 op_sel_hi:[1,0]
	v_pk_add_f32 v[150:151], v[150:151], 1.0 op_sel_hi:[1,0]
	v_pk_add_f32 v[152:153], v[152:153], 1.0 op_sel_hi:[1,0]
	v_pk_add_f32 v[154:155], v[154:155], 1.0 op_sel_hi:[1,0]
	v_pk_add_f32 v[156:157], v[156:157], 1.0 op_sel_hi:[1,0]
	v_pk_add_f32 v[158:159], v[158:159], 1.0 op_sel_hi:[1,0]
	v_pk_add_f32 v[160:161], v[160:161], 1.0 op_sel_hi:[1,0]
	v_pk_mul_f32 v[130:131], v[130:131], v[146:147]
	v_pk_mul_f32 v[132:133], v[132:133], v[148:149]
	v_pk_mul_f32 v[134:135], v[134:135], v[150:151]
	v_pk_mul_f32 v[136:137], v[136:137], v[152:153]
	v_pk_mul_f32 v[138:139], v[138:139], v[154:155]
	v_pk_mul_f32 v[140:141], v[140:141], v[156:157]
	v_pk_mul_f32 v[142:143], v[142:143], v[158:159]
	v_pk_mul_f32 v[144:145], v[144:145], v[160:161]
	s_barrier
	v_lshl_add_u32 v210, v212, 4, 0
	s_lshl_b32 s48, s25, 4
	v_add_u32_e32 v210, s48, v210
	s_cmp_eq_u32 s49, 1
	s_cbranch_scc1 .Lmy_tail_l2
	s_mov_b32 s44, s42
	s_mov_b32 s45, s43
	global_load_dwordx4 v[146:149], v210, s[44:45] sc1
	global_load_dwordx4 v[196:199], v210, s[44:45] offset:2048 sc1
	s_add_u32 s44, s44, 0x40000
	s_addc_u32 s45, s45, 0
	global_load_dwordx4 v[150:153], v210, s[44:45] sc1
	global_load_dwordx4 v[200:203], v210, s[44:45] offset:2048 sc1
	s_add_u32 s44, s44, 0x40000
	s_addc_u32 s45, s45, 0
	global_load_dwordx4 v[154:157], v210, s[44:45] sc1
	global_load_dwordx4 v[204:207], v210, s[44:45] offset:2048 sc1
	s_add_u32 s44, s44, 0x40000
	s_addc_u32 s45, s45, 0
	global_load_dwordx4 v[158:161], v210, s[44:45] sc1
	global_load_dwordx4 v[192:195], v210, s[44:45] offset:2048 sc1
	s_branch .Lmy_tail_ld
.Lmy_tail_l2:
	s_mov_b32 s44, s42
	s_mov_b32 s45, s43
	global_load_dwordx4 v[146:149], v210, s[44:45]
	global_load_dwordx4 v[196:199], v210, s[44:45] offset:2048
	s_add_u32 s44, s44, 0x40000
	s_addc_u32 s45, s45, 0
	global_load_dwordx4 v[150:153], v210, s[44:45]
	global_load_dwordx4 v[200:203], v210, s[44:45] offset:2048
	s_add_u32 s44, s44, 0x40000
	s_addc_u32 s45, s45, 0
	global_load_dwordx4 v[154:157], v210, s[44:45]
	global_load_dwordx4 v[204:207], v210, s[44:45] offset:2048
	s_add_u32 s44, s44, 0x40000
	s_addc_u32 s45, s45, 0
	global_load_dwordx4 v[158:161], v210, s[44:45]
	global_load_dwordx4 v[192:195], v210, s[44:45] offset:2048
.Lmy_tail_ld:
	s_waitcnt vmcnt(0)
	v_add_f32_e32 v208, v146, v147
	v_add_f32_e32 v210, v148, v149
	v_add_f32_e32 v208, v208, v210
	v_add_f32_e32 v208, 0, v208
	v_add_f32_e32 v211, v150, v151
	v_add_f32_e32 v210, v152, v153
	v_add_f32_e32 v210, v211, v210
	v_add_f32_e32 v208, v208, v210
	v_add_f32_e32 v211, v154, v155
	v_add_f32_e32 v210, v156, v157
	v_add_f32_e32 v210, v211, v210
	v_add_f32_e32 v208, v208, v210
	v_add_f32_e32 v211, v158, v159
	v_add_f32_e32 v210, v160, v161
	v_add_f32_e32 v210, v211, v210
	v_add_f32_e32 v208, v208, v210
	v_fmamk_f32 v208, v208, 0x3a800000, v216
	v_cmp_gt_f32_e32 vcc, s0, v208
	v_mul_f32_e32 v210, 0x4b800000, v208
	s_nop 0
	v_cndmask_b32_e32 v208, v208, v210, vcc
	v_rsq_f32_e32 v208, v208
	s_nop 0
	v_mul_f32_e32 v210, 0x45800000, v208
	v_cndmask_b32_e32 v208, v208, v210, vcc
	v_add_f32_e32 v209, v196, v197
	v_add_f32_e32 v210, v198, v199
	v_add_f32_e32 v209, v209, v210
	v_add_f32_e32 v209, 0, v209
	v_add_f32_e32 v211, v200, v201
	v_add_f32_e32 v210, v202, v203
	v_add_f32_e32 v210, v211, v210
	v_add_f32_e32 v209, v209, v210
	v_add_f32_e32 v211, v204, v205
	v_add_f32_e32 v210, v206, v207
	v_add_f32_e32 v210, v211, v210
	v_add_f32_e32 v209, v209, v210
	v_add_f32_e32 v211, v192, v193
	v_add_f32_e32 v210, v194, v195
	v_add_f32_e32 v210, v211, v210
	v_add_f32_e32 v209, v209, v210
	v_fmamk_f32 v209, v209, 0x3a800000, v216
	v_cmp_gt_f32_e32 vcc, s0, v209
	v_mul_f32_e32 v210, 0x4b800000, v209
	s_nop 0
	v_cndmask_b32_e32 v209, v209, v210, vcc
	v_rsq_f32_e32 v209, v209
	s_nop 0
	v_mul_f32_e32 v210, 0x45800000, v209
	v_cndmask_b32_e32 v209, v209, v210, vcc
	v_lshlrev_b32_e32 v206, 2, v213
	v_add_u32_e32 v201, 64, v206
	v_add_u32_e32 v202, 128, v206
	v_add_u32_e32 v203, 192, v206
	ds_bpermute_b32 v180, v206, v208
	ds_bpermute_b32 v188, v206, v209
	ds_bpermute_b32 v182, v201, v208
	ds_bpermute_b32 v190, v201, v209
	ds_bpermute_b32 v184, v202, v208
	ds_bpermute_b32 v192, v202, v209
	ds_bpermute_b32 v186, v203, v208
	ds_bpermute_b32 v194, v203, v209
	v_lshlrev_b32_e32 v204, 11, v213
	v_lshl_add_u32 v204, v215, 1, v204
	s_waitcnt lgkmcnt(0)
; __device__ __forceinline__ unsigned pk2(float lo, float hi) { f32x2_t v = {lo, hi}; bf16x2_t b = __builtin_convertvector(v, bf16x2_t); return __builtin_bit_cast(unsigned, b); }
; __device__ __forceinline__ void fused_norm_tail(CA& A, int l, int s) {
;     ...
; #pragma unroll
;     for (int r = 0; r < 32; ++r) {
;         const int row = u.pm * 256 + wave * 32 + r;
;         const float rstd = __builtin_bit_cast(float, __builtin_amdgcn_readlane(__builtin_bit_cast(int, rstd_l), r));
;         const f32x4 y = hrow[r] * rstd * ca + cb;
;         v2u o; o.x = pk2(y.x, y.y); o.y = pk2(y.z, y.w);
;         *(v2u*)(xn + (size_t)row * DM + col) = o;
;     }
	s_add_u32 s40, s38, 0x0
	s_addc_u32 s41, s39, 0
	v_pk_mul_f32 v[126:127], v[126:127], v[180:181] op_sel_hi:[1,0]
	v_pk_mul_f32 v[128:129], v[128:129], v[180:181] op_sel_hi:[1,0]
	v_pk_mul_f32 v[122:123], v[122:123], v[180:181] op_sel_hi:[1,0]
	v_pk_mul_f32 v[124:125], v[124:125], v[180:181] op_sel_hi:[1,0]
	v_pk_fma_f32 v[126:127], v[130:131], v[126:127], v[162:163]
	v_pk_fma_f32 v[128:129], v[132:133], v[128:129], v[164:165]
	v_pk_fma_f32 v[122:123], v[134:135], v[122:123], v[166:167]
	v_pk_fma_f32 v[124:125], v[136:137], v[124:125], v[168:169]
	v_cvt_pk_bf16_f32 v126, v126, v127
	v_cvt_pk_bf16_f32 v127, v128, v129
	v_cvt_pk_bf16_f32 v128, v122, v123
	v_cvt_pk_bf16_f32 v129, v124, v125
	global_store_dwordx4 v204, v[126:129], s[40:41]
	v_pk_mul_f32 v[118:119], v[118:119], v[180:181] op_sel_hi:[1,0]
	v_pk_mul_f32 v[120:121], v[120:121], v[180:181] op_sel_hi:[1,0]
	v_pk_mul_f32 v[114:115], v[114:115], v[180:181] op_sel_hi:[1,0]
	v_pk_mul_f32 v[116:117], v[116:117], v[180:181] op_sel_hi:[1,0]
	v_pk_fma_f32 v[118:119], v[138:139], v[118:119], v[170:171]
	v_pk_fma_f32 v[120:121], v[140:141], v[120:121], v[172:173]
	v_pk_fma_f32 v[114:115], v[142:143], v[114:115], v[174:175]
	v_pk_fma_f32 v[116:117], v[144:145], v[116:117], v[176:177]
	v_cvt_pk_bf16_f32 v118, v118, v119
	v_cvt_pk_bf16_f32 v119, v120, v121
	v_cvt_pk_bf16_f32 v120, v114, v115
	v_cvt_pk_bf16_f32 v121, v116, v117
	global_store_dwordx4 v204, v[118:121], s[40:41] offset:256
	s_add_u32 s40, s38, 0x8000
	s_addc_u32 s41, s39, 0
	v_pk_mul_f32 v[110:111], v[110:111], v[182:183] op_sel_hi:[1,0]
	v_pk_mul_f32 v[112:113], v[112:113], v[182:183] op_sel_hi:[1,0]
	v_pk_mul_f32 v[106:107], v[106:107], v[182:183] op_sel_hi:[1,0]
	v_pk_mul_f32 v[108:109], v[108:109], v[182:183] op_sel_hi:[1,0]
	v_pk_fma_f32 v[110:111], v[130:131], v[110:111], v[162:163]
	v_pk_fma_f32 v[112:113], v[132:133], v[112:113], v[164:165]
	v_pk_fma_f32 v[106:107], v[134:135], v[106:107], v[166:167]
	v_pk_fma_f32 v[108:109], v[136:137], v[108:109], v[168:169]
	v_cvt_pk_bf16_f32 v110, v110, v111
	v_cvt_pk_bf16_f32 v111, v112, v113
	v_cvt_pk_bf16_f32 v112, v106, v107
	v_cvt_pk_bf16_f32 v113, v108, v109
	global_store_dwordx4 v204, v[110:113], s[40:41]
	v_pk_mul_f32 v[102:103], v[102:103], v[182:183] op_sel_hi:[1,0]
	v_pk_mul_f32 v[104:105], v[104:105], v[182:183] op_sel_hi:[1,0]
	v_pk_mul_f32 v[98:99], v[98:99], v[182:183] op_sel_hi:[1,0]
	v_pk_mul_f32 v[100:101], v[100:101], v[182:183] op_sel_hi:[1,0]
	v_pk_fma_f32 v[102:103], v[138:139], v[102:103], v[170:171]
	v_pk_fma_f32 v[104:105], v[140:141], v[104:105], v[172:173]
	v_pk_fma_f32 v[98:99], v[142:143], v[98:99], v[174:175]
	v_pk_fma_f32 v[100:101], v[144:145], v[100:101], v[176:177]
	v_cvt_pk_bf16_f32 v102, v102, v103
	v_cvt_pk_bf16_f32 v103, v104, v105
	v_cvt_pk_bf16_f32 v104, v98, v99
	v_cvt_pk_bf16_f32 v105, v100, v101
	global_store_dwordx4 v204, v[102:105], s[40:41] offset:256
	s_add_u32 s40, s38, 0x10000
	s_addc_u32 s41, s39, 0
	v_pk_mul_f32 v[94:95], v[94:95], v[184:185] op_sel_hi:[1,0]
	v_pk_mul_f32 v[96:97], v[96:97], v[184:185] op_sel_hi:[1,0]
	v_pk_mul_f32 v[90:91], v[90:91], v[184:185] op_sel_hi:[1,0]
	v_pk_mul_f32 v[92:93], v[92:93], v[184:185] op_sel_hi:[1,0]
	v_pk_fma_f32 v[94:95], v[130:131], v[94:95], v[162:163]
	v_pk_fma_f32 v[96:97], v[132:133], v[96:97], v[164:165]
	v_pk_fma_f32 v[90:91], v[134:135], v[90:91], v[166:167]
	v_pk_fma_f32 v[92:93], v[136:137], v[92:93], v[168:169]
	v_cvt_pk_bf16_f32 v94, v94, v95
	v_cvt_pk_bf16_f32 v95, v96, v97
	v_cvt_pk_bf16_f32 v96, v90, v91
	v_cvt_pk_bf16_f32 v97, v92, v93
	global_store_dwordx4 v204, v[94:97], s[40:41]
	v_pk_mul_f32 v[86:87], v[86:87], v[184:185] op_sel_hi:[1,0]
	v_pk_mul_f32 v[88:89], v[88:89], v[184:185] op_sel_hi:[1,0]
	v_pk_mul_f32 v[82:83], v[82:83], v[184:185] op_sel_hi:[1,0]
	v_pk_mul_f32 v[84:85], v[84:85], v[184:185] op_sel_hi:[1,0]
	v_pk_fma_f32 v[86:87], v[138:139], v[86:87], v[170:171]
	v_pk_fma_f32 v[88:89], v[140:141], v[88:89], v[172:173]
	v_pk_fma_f32 v[82:83], v[142:143], v[82:83], v[174:175]
	v_pk_fma_f32 v[84:85], v[144:145], v[84:85], v[176:177]
	v_cvt_pk_bf16_f32 v86, v86, v87
	v_cvt_pk_bf16_f32 v87, v88, v89
	v_cvt_pk_bf16_f32 v88, v82, v83
	v_cvt_pk_bf16_f32 v89, v84, v85
	global_store_dwordx4 v204, v[86:89], s[40:41] offset:256
	s_add_u32 s40, s38, 0x18000
	s_addc_u32 s41, s39, 0
	v_pk_mul_f32 v[78:79], v[78:79], v[186:187] op_sel_hi:[1,0]
	v_pk_mul_f32 v[80:81], v[80:81], v[186:187] op_sel_hi:[1,0]
	v_pk_mul_f32 v[74:75], v[74:75], v[186:187] op_sel_hi:[1,0]
	v_pk_mul_f32 v[76:77], v[76:77], v[186:187] op_sel_hi:[1,0]
	v_pk_fma_f32 v[78:79], v[130:131], v[78:79], v[162:163]
	v_pk_fma_f32 v[80:81], v[132:133], v[80:81], v[164:165]
	v_pk_fma_f32 v[74:75], v[134:135], v[74:75], v[166:167]
	v_pk_fma_f32 v[76:77], v[136:137], v[76:77], v[168:169]
	v_cvt_pk_bf16_f32 v78, v78, v79
	v_cvt_pk_bf16_f32 v79, v80, v81
	v_cvt_pk_bf16_f32 v80, v74, v75
	v_cvt_pk_bf16_f32 v81, v76, v77
	global_store_dwordx4 v204, v[78:81], s[40:41]
	v_pk_mul_f32 v[70:71], v[70:71], v[186:187] op_sel_hi:[1,0]
	v_pk_mul_f32 v[72:73], v[72:73], v[186:187] op_sel_hi:[1,0]
	v_pk_mul_f32 v[66:67], v[66:67], v[186:187] op_sel_hi:[1,0]
	v_pk_mul_f32 v[68:69], v[68:69], v[186:187] op_sel_hi:[1,0]
	v_pk_fma_f32 v[70:71], v[138:139], v[70:71], v[170:171]
	v_pk_fma_f32 v[72:73], v[140:141], v[72:73], v[172:173]
	v_pk_fma_f32 v[66:67], v[142:143], v[66:67], v[174:175]
	v_pk_fma_f32 v[68:69], v[144:145], v[68:69], v[176:177]
	v_cvt_pk_bf16_f32 v70, v70, v71
	v_cvt_pk_bf16_f32 v71, v72, v73
; __device__ __forceinline__ unsigned pk2(float lo, float hi) { f32x2_t v = {lo, hi}; bf16x2_t b = __builtin_convertvector(v, bf16x2_t); return __builtin_bit_cast(unsigned, b); }
; __device__ __forceinline__ void fused_norm_tail(CA& A, int l, int s) {
;     ...
; #pragma unroll
;     for (int r = 0; r < 32; ++r) {
;         const int row = u.pm * 256 + wave * 32 + r;
;         const float rstd = __builtin_bit_cast(float, __builtin_amdgcn_readlane(__builtin_bit_cast(int, rstd_l), r));
;         const f32x4 y = hrow[r] * rstd * ca + cb;
;         v2u o; o.x = pk2(y.x, y.y); o.y = pk2(y.z, y.w);
;         *(v2u*)(xn + (size_t)row * DM + col) = o;
;     }
	v_cvt_pk_bf16_f32 v72, v66, v67
	v_cvt_pk_bf16_f32 v73, v68, v69
	global_store_dwordx4 v204, v[70:73], s[40:41] offset:256
	s_add_u32 s40, s38, 0x40000
	s_addc_u32 s41, s39, 0
	v_pk_mul_f32 v[62:63], v[62:63], v[188:189] op_sel_hi:[1,0]
	v_pk_mul_f32 v[64:65], v[64:65], v[188:189] op_sel_hi:[1,0]
	v_pk_mul_f32 v[58:59], v[58:59], v[188:189] op_sel_hi:[1,0]
	v_pk_mul_f32 v[60:61], v[60:61], v[188:189] op_sel_hi:[1,0]
	v_pk_fma_f32 v[62:63], v[130:131], v[62:63], v[162:163]
	v_pk_fma_f32 v[64:65], v[132:133], v[64:65], v[164:165]
	v_pk_fma_f32 v[58:59], v[134:135], v[58:59], v[166:167]
	v_pk_fma_f32 v[60:61], v[136:137], v[60:61], v[168:169]
	v_cvt_pk_bf16_f32 v62, v62, v63
	v_cvt_pk_bf16_f32 v63, v64, v65
	v_cvt_pk_bf16_f32 v64, v58, v59
	v_cvt_pk_bf16_f32 v65, v60, v61
	global_store_dwordx4 v204, v[62:65], s[40:41]
	v_pk_mul_f32 v[54:55], v[54:55], v[188:189] op_sel_hi:[1,0]
	v_pk_mul_f32 v[56:57], v[56:57], v[188:189] op_sel_hi:[1,0]
	v_pk_mul_f32 v[50:51], v[50:51], v[188:189] op_sel_hi:[1,0]
	v_pk_mul_f32 v[52:53], v[52:53], v[188:189] op_sel_hi:[1,0]
	v_pk_fma_f32 v[54:55], v[138:139], v[54:55], v[170:171]
	v_pk_fma_f32 v[56:57], v[140:141], v[56:57], v[172:173]
	v_pk_fma_f32 v[50:51], v[142:143], v[50:51], v[174:175]
	v_pk_fma_f32 v[52:53], v[144:145], v[52:53], v[176:177]
	v_cvt_pk_bf16_f32 v54, v54, v55
	v_cvt_pk_bf16_f32 v55, v56, v57
	v_cvt_pk_bf16_f32 v56, v50, v51
	v_cvt_pk_bf16_f32 v57, v52, v53
	global_store_dwordx4 v204, v[54:57], s[40:41] offset:256
	s_add_u32 s40, s38, 0x48000
	s_addc_u32 s41, s39, 0
	v_pk_mul_f32 v[46:47], v[46:47], v[190:191] op_sel_hi:[1,0]
	v_pk_mul_f32 v[48:49], v[48:49], v[190:191] op_sel_hi:[1,0]
	v_pk_mul_f32 v[42:43], v[42:43], v[190:191] op_sel_hi:[1,0]
	v_pk_mul_f32 v[44:45], v[44:45], v[190:191] op_sel_hi:[1,0]
	v_pk_fma_f32 v[46:47], v[130:131], v[46:47], v[162:163]
	v_pk_fma_f32 v[48:49], v[132:133], v[48:49], v[164:165]
	v_pk_fma_f32 v[42:43], v[134:135], v[42:43], v[166:167]
	v_pk_fma_f32 v[44:45], v[136:137], v[44:45], v[168:169]
	v_cvt_pk_bf16_f32 v46, v46, v47
	v_cvt_pk_bf16_f32 v47, v48, v49
	v_cvt_pk_bf16_f32 v48, v42, v43
	v_cvt_pk_bf16_f32 v49, v44, v45
	global_store_dwordx4 v204, v[46:49], s[40:41]
	v_pk_mul_f32 v[38:39], v[38:39], v[190:191] op_sel_hi:[1,0]
	v_pk_mul_f32 v[40:41], v[40:41], v[190:191] op_sel_hi:[1,0]
	v_pk_mul_f32 v[34:35], v[34:35], v[190:191] op_sel_hi:[1,0]
	v_pk_mul_f32 v[36:37], v[36:37], v[190:191] op_sel_hi:[1,0]
	v_pk_fma_f32 v[38:39], v[138:139], v[38:39], v[170:171]
	v_pk_fma_f32 v[40:41], v[140:141], v[40:41], v[172:173]
	v_pk_fma_f32 v[34:35], v[142:143], v[34:35], v[174:175]
	v_pk_fma_f32 v[36:37], v[144:145], v[36:37], v[176:177]
	v_cvt_pk_bf16_f32 v38, v38, v39
	v_cvt_pk_bf16_f32 v39, v40, v41
	v_cvt_pk_bf16_f32 v40, v34, v35
	v_cvt_pk_bf16_f32 v41, v36, v37
	global_store_dwordx4 v204, v[38:41], s[40:41] offset:256
	s_add_u32 s40, s38, 0x50000
	s_addc_u32 s41, s39, 0
	v_pk_mul_f32 v[30:31], v[30:31], v[192:193] op_sel_hi:[1,0]
	v_pk_mul_f32 v[32:33], v[32:33], v[192:193] op_sel_hi:[1,0]
	v_pk_mul_f32 v[26:27], v[26:27], v[192:193] op_sel_hi:[1,0]
	v_pk_mul_f32 v[28:29], v[28:29], v[192:193] op_sel_hi:[1,0]
	v_pk_fma_f32 v[30:31], v[130:131], v[30:31], v[162:163]
	v_pk_fma_f32 v[32:33], v[132:133], v[32:33], v[164:165]
	v_pk_fma_f32 v[26:27], v[134:135], v[26:27], v[166:167]
	v_pk_fma_f32 v[28:29], v[136:137], v[28:29], v[168:169]
	v_cvt_pk_bf16_f32 v30, v30, v31
	v_cvt_pk_bf16_f32 v31, v32, v33
	v_cvt_pk_bf16_f32 v32, v26, v27
	v_cvt_pk_bf16_f32 v33, v28, v29
	global_store_dwordx4 v204, v[30:33], s[40:41]
	v_pk_mul_f32 v[22:23], v[22:23], v[192:193] op_sel_hi:[1,0]
	v_pk_mul_f32 v[24:25], v[24:25], v[192:193] op_sel_hi:[1,0]
	v_pk_mul_f32 v[18:19], v[18:19], v[192:193] op_sel_hi:[1,0]
	v_pk_mul_f32 v[20:21], v[20:21], v[192:193] op_sel_hi:[1,0]
	v_pk_fma_f32 v[22:23], v[138:139], v[22:23], v[170:171]
	v_pk_fma_f32 v[24:25], v[140:141], v[24:25], v[172:173]
	v_pk_fma_f32 v[18:19], v[142:143], v[18:19], v[174:175]
	v_pk_fma_f32 v[20:21], v[144:145], v[20:21], v[176:177]
	v_cvt_pk_bf16_f32 v22, v22, v23
	v_cvt_pk_bf16_f32 v23, v24, v25
	v_cvt_pk_bf16_f32 v24, v18, v19
	v_cvt_pk_bf16_f32 v25, v20, v21
	global_store_dwordx4 v204, v[22:25], s[40:41] offset:256
	s_add_u32 s40, s38, 0x58000
	s_addc_u32 s41, s39, 0
	v_pk_mul_f32 v[14:15], v[14:15], v[194:195] op_sel_hi:[1,0]
	v_pk_mul_f32 v[16:17], v[16:17], v[194:195] op_sel_hi:[1,0]
	v_pk_mul_f32 v[10:11], v[10:11], v[194:195] op_sel_hi:[1,0]
	v_pk_mul_f32 v[12:13], v[12:13], v[194:195] op_sel_hi:[1,0]
	v_pk_fma_f32 v[14:15], v[130:131], v[14:15], v[162:163]
	v_pk_fma_f32 v[16:17], v[132:133], v[16:17], v[164:165]
	v_pk_fma_f32 v[10:11], v[134:135], v[10:11], v[166:167]
	v_pk_fma_f32 v[12:13], v[136:137], v[12:13], v[168:169]
	v_cvt_pk_bf16_f32 v14, v14, v15
	v_cvt_pk_bf16_f32 v15, v16, v17
	v_cvt_pk_bf16_f32 v16, v10, v11
	v_cvt_pk_bf16_f32 v17, v12, v13
	global_store_dwordx4 v204, v[14:17], s[40:41]
	v_pk_mul_f32 v[6:7], v[6:7], v[194:195] op_sel_hi:[1,0]
	v_pk_mul_f32 v[8:9], v[8:9], v[194:195] op_sel_hi:[1,0]
	v_pk_mul_f32 v[2:3], v[2:3], v[194:195] op_sel_hi:[1,0]
	v_pk_mul_f32 v[4:5], v[4:5], v[194:195] op_sel_hi:[1,0]
	v_pk_fma_f32 v[6:7], v[138:139], v[6:7], v[170:171]
	v_pk_fma_f32 v[8:9], v[140:141], v[8:9], v[172:173]
	v_pk_fma_f32 v[2:3], v[142:143], v[2:3], v[174:175]
	v_pk_fma_f32 v[4:5], v[144:145], v[4:5], v[176:177]
	v_cvt_pk_bf16_f32 v6, v6, v7
	v_cvt_pk_bf16_f32 v7, v8, v9
	v_cvt_pk_bf16_f32 v8, v2, v3
	v_cvt_pk_bf16_f32 v9, v4, v5
	global_store_dwordx4 v204, v[6:9], s[40:41] offset:256
